# idle-slot deferral: FFN weight transposes of layers 1-3 at the W1/WinA GEMM exits (long idle slots), cache_ckv j=1 conversion at the FFN-up 9th-round idle slots of layers 0/1
# speedup vs baseline: 1.0179x; 1.0020x over previous
.LBB0_13:
	s_load_dwordx4 s[4:7], s[86:87], 0xb0
	s_waitcnt lgkmcnt(0)
	s_cmp_lt_i32 s6, 1
	s_cselect_b64 s[2:3], -1, 0
	s_cmp_gt_i32 s7, 0
	s_cselect_b64 s[4:5], -1, 0
	s_and_b64 s[4:5], s[2:3], s[4:5]
	s_andn2_b64 vcc, exec, s[4:5]
	s_cbranch_vccnz .LBB0_273
	s_load_dword s58, s[86:87], 0xc0
	v_readlane_b32 s46, v254, 0
	s_mov_b64 s[20:21], s[86:87]
	s_waitcnt lgkmcnt(0)
	s_load_dwordx2 s[16:17], s[20:21], 0xb0
	v_mov_b32_e32 v47, v0
	s_lshl_b32 s18, s46, 3
	v_readfirstlane_b32 s4, v47
	s_ashr_i32 s14, s4, 6
	s_add_i32 s22, s14, s18
	s_lshl_b32 s12, s58, 3
	s_waitcnt lgkmcnt(0)
	s_add_u32 s26, s16, 0x27b32000
	s_addc_u32 s27, s17, 0
	s_cmp_gt_i32 s22, 0x1ffff
	v_and_b32_e32 v1, 63, v47
	s_cbranch_scc1 .LBB0_29
	s_load_dwordx2 s[4:5], s[20:21], 0x10
	s_ashr_i32 s13, s12, 31
	v_lshlrev_b32_e32 v2, 5, v1
	v_mov_b32_e32 v3, 0
	s_ashr_i32 s15, s14, 31
	s_ashr_i32 s19, s18, 31
	s_ashr_i32 s23, s22, 31
	s_waitcnt lgkmcnt(0)
	v_lshl_add_u64 v[34:35], s[4:5], 0, v[2:3]
	s_lshl_b64 s[10:11], s[12:13], 1
	s_lshl_b64 s[4:5], s[14:15], 11
	s_lshl_b64 s[6:7], s[18:19], 11
	s_add_u32 s24, s4, s6
	s_addc_u32 s25, s5, s7
	s_lshl_b64 s[28:29], s[12:13], 13
	s_add_u32 s6, s14, s18
	s_addc_u32 s7, s15, s19
	s_add_u32 s4, s6, s10
	s_addc_u32 s5, s7, s11
	s_lshl_b64 s[30:31], s[4:5], 11
	s_or_b32 s30, s30, 16
	s_add_u32 s4, s6, s12
	s_addc_u32 s5, s7, s13
	s_mul_i32 s19, s12, 3
	s_lshl_b64 s[34:35], s[4:5], 11
	s_mul_hi_i32 s15, s12, 3
	s_add_u32 s4, s6, s19
	s_addc_u32 s5, s7, s15
	v_lshlrev_b32_e32 v2, 4, v1
	s_lshl_b64 s[36:37], s[4:5], 11
	v_lshl_add_u64 v[36:37], s[26:27], 0, v[2:3]
	s_or_b32 s36, s36, 16
	v_mov_b64_e32 v[38:39], 0x20000
	v_mov_b64_e32 v[40:41], 0x1ffff
	v_mov_b32_e32 v42, 0x500
	s_mov_b64 s[40:41], s[22:23]
	v_mov_b32_e32 v2, v3
	v_mov_b32_e32 v4, v3
	v_mov_b32_e32 v5, v3
	v_mov_b32_e32 v6, v3
	v_mov_b32_e32 v7, v3
	v_mov_b32_e32 v8, v3
	v_mov_b32_e32 v9, v3
	v_mov_b32_e32 v14, v3
	v_mov_b32_e32 v15, v3
	v_mov_b32_e32 v16, v3
	v_mov_b32_e32 v17, v3
	v_mov_b32_e32 v10, v3
	v_mov_b32_e32 v11, v3
	v_mov_b32_e32 v12, v3
	v_mov_b32_e32 v13, v3
	v_mov_b32_e32 v18, v3
	v_mov_b32_e32 v19, v3
	v_mov_b32_e32 v20, v3
	v_mov_b32_e32 v21, v3
	v_mov_b32_e32 v22, v3
	v_mov_b32_e32 v23, v3
	v_mov_b32_e32 v24, v3
	v_mov_b32_e32 v25, v3
	s_branch .LBB0_17

.LBB0_412:
	s_waitcnt vmcnt(0)
	v_readlane_b32 s86, v255, 26
	v_readlane_b32 s54, v255, 36
	v_readlane_b32 s87, v255, 27
	v_readlane_b32 s55, v255, 37
	s_barrier
	s_mov_b64 s[98:99], exec
	s_mov_b64 exec, -1
	v_readlane_b32 s2, v254, 0
	v_readlane_b32 s3, v255, 24
	s_load_dword s4, s[86:87], 0xc0
	s_waitcnt lgkmcnt(0)
	s_cmp_eq_u32 s3, 1
	s_cbranch_scc0 .Ldm8_sel0
	s_mov_b32 s69, 2
	s_mov_b32 s79, 3
	s_branch .Ldm8_go

.Ldm8_go:
	s_cmp_eq_u32 s4, 0x100
	s_cbranch_scc0 .Ldm8_all
	s_cmp_lt_u32 s2, 96
	s_cbranch_scc1 .Ldm8_done
	s_sub_u32 s2, s2, 96
	s_movk_i32 s4, 160
.Ldm8_all:
	v_readfirstlane_b32 s5, v0
	s_lshr_b32 s5, s5, 6
	s_lshl_b32 s2, s2, 3
	s_add_u32 s2, s2, s5
	s_lshl_b32 s92, s4, 3
	v_mbcnt_lo_u32_b32 v41, -1, 0
	v_mbcnt_hi_u32_b32 v41, -1, v41
	v_lshrrev_b32_e32 v42, 3, v41
	v_and_b32_e32 v43, 7, v41
	v_lshlrev_b32_e32 v44, 13, v42
	v_lshl_add_u32 v44, v43, 4, v44
	v_add_u32_e32 v45, 0x10000, v44
	v_add_u32_e32 v46, 0x20000, v44
	v_add_u32_e32 v47, 0x30000, v44
	v_add_u32_e32 v48, 0x40000, v44
	v_add_u32_e32 v49, 0x50000, v44
	v_add_u32_e32 v50, 0x60000, v44
	v_add_u32_e32 v51, 0x70000, v44
	s_lshl_b32 s49, s5, 14
	v_mul_u32_u24_e32 v52, 0x84, v42
	v_lshl_add_u32 v52, v43, 4, v52
	v_add_u32_e32 v52, s49, v52
	v_mul_u32_u24_e32 v53, 0x420, v43
	v_lshl_add_u32 v53, v42, 2, v53
	v_add_u32_e32 v53, s49, v53
	v_lshlrev_b32_e32 v54, 14, v42
	v_lshl_add_u32 v54, v43, 4, v54
	v_add_u32_e32 v55, 0x20000, v54
	v_add_u32_e32 v56, 0x40000, v54
	v_add_u32_e32 v57, 0x60000, v54
.Ldm8_job:
	s_mov_b32 s91, s2
	s_cmp_ge_u32 s91, 0x2000
	s_cbranch_scc1 .Ldm8_done
	s_load_dwordx2 s[6:7], s[86:87], 0x98
	s_load_dwordx2 s[88:89], s[86:87], 0xb0
	s_lshl_b32 s48, s69, 26
	s_waitcnt lgkmcnt(0)
	s_add_u32 s6, s6, s48
	s_addc_u32 s7, s7, 0
	s_lshl_b32 s48, s69, 25
	s_add_u32 s88, s88, 0x76b32000
	s_addc_u32 s89, s89, 0
	s_add_u32 s88, s88, s48
	s_addc_u32 s89, s89, 0
	s_lshr_b32 s72, s91, 6
	s_and_b32 s73, s91, 63
	s_lshl_b32 s56, s72, 19
	s_lshl_b32 s57, s73, 7
	s_add_u32 s56, s56, s57
	s_add_u32 s50, s6, s56
	s_addc_u32 s51, s7, 0
	global_load_dwordx4 v[58:61], v44, s[50:51] nt
	global_load_dwordx4 v[62:65], v45, s[50:51] nt
	global_load_dwordx4 v[66:69], v46, s[50:51] nt
	global_load_dwordx4 v[70:73], v47, s[50:51] nt
	global_load_dwordx4 v[74:77], v48, s[50:51] nt
	global_load_dwordx4 v[78:81], v49, s[50:51] nt
	global_load_dwordx4 v[82:85], v50, s[50:51] nt
	global_load_dwordx4 v[86:89], v51, s[50:51] nt
	s_add_u32 s71, s91, s92
	s_cmp_ge_u32 s71, 0x2000
	s_cbranch_scc1 .Ldm8_first0
	s_lshr_b32 s72, s71, 6
	s_and_b32 s73, s71, 63
	s_lshl_b32 s56, s72, 19
	s_lshl_b32 s57, s73, 7
	s_add_u32 s56, s56, s57
	s_add_u32 s50, s6, s56
	s_addc_u32 s51, s7, 0
	global_load_dwordx4 v[90:93], v44, s[50:51] nt
	global_load_dwordx4 v[94:97], v45, s[50:51] nt
	global_load_dwordx4 v[98:101], v46, s[50:51] nt
	global_load_dwordx4 v[102:105], v47, s[50:51] nt
	global_load_dwordx4 v[106:109], v48, s[50:51] nt
	global_load_dwordx4 v[110:113], v49, s[50:51] nt
	global_load_dwordx4 v[114:117], v50, s[50:51] nt
	global_load_dwordx4 v[118:121], v51, s[50:51] nt
	s_waitcnt vmcnt(8)
	s_branch .Ldm8_loop

.Ldm8_loop:
	s_lshr_b32 s72, s91, 6
	s_and_b32 s73, s91, 63
	s_lshl_b32 s58, s73, 19
	s_lshl_b32 s59, s72, 7
	s_add_u32 s58, s58, s59
	ds_write_b32 v52, v58 offset:0
	ds_write_b32 v52, v59 offset:4
	ds_write_b32 v52, v60 offset:8
	ds_write_b32 v52, v61 offset:12
	ds_write_b32 v52, v62 offset:1056
	ds_write_b32 v52, v63 offset:1060
	ds_write_b32 v52, v64 offset:1064
	ds_write_b32 v52, v65 offset:1068
	ds_write_b32 v52, v66 offset:2112
	ds_write_b32 v52, v67 offset:2116
	ds_write_b32 v52, v68 offset:2120
	ds_write_b32 v52, v69 offset:2124
	ds_write_b32 v52, v70 offset:3168
	ds_write_b32 v52, v71 offset:3172
	ds_write_b32 v52, v72 offset:3176
	ds_write_b32 v52, v73 offset:3180
	ds_write_b32 v52, v74 offset:4224
	ds_write_b32 v52, v75 offset:4228
	ds_write_b32 v52, v76 offset:4232
	ds_write_b32 v52, v77 offset:4236
	ds_write_b32 v52, v78 offset:5280
	ds_write_b32 v52, v79 offset:5284
	ds_write_b32 v52, v80 offset:5288
	ds_write_b32 v52, v81 offset:5292
	ds_write_b32 v52, v82 offset:6336
	ds_write_b32 v52, v83 offset:6340
	ds_write_b32 v52, v84 offset:6344
	ds_write_b32 v52, v85 offset:6348
	ds_write_b32 v52, v86 offset:7392
	ds_write_b32 v52, v87 offset:7396
	ds_write_b32 v52, v88 offset:7400
	ds_write_b32 v52, v89 offset:7404
	s_waitcnt lgkmcnt(0)
	s_add_u32 s91, s71, s92
	s_cmp_ge_u32 s91, 0x2000
	s_cbranch_scc1 .Ldm8_nopfa
	s_lshr_b32 s72, s91, 6
	s_and_b32 s73, s91, 63
	s_lshl_b32 s56, s72, 19
	s_lshl_b32 s57, s73, 7
	s_add_u32 s56, s56, s57
	s_add_u32 s50, s6, s56
	s_addc_u32 s51, s7, 0
	global_load_dwordx4 v[58:61], v44, s[50:51] nt
	global_load_dwordx4 v[62:65], v45, s[50:51] nt
	global_load_dwordx4 v[66:69], v46, s[50:51] nt
	global_load_dwordx4 v[70:73], v47, s[50:51] nt
	global_load_dwordx4 v[74:77], v48, s[50:51] nt
	global_load_dwordx4 v[78:81], v49, s[50:51] nt
	global_load_dwordx4 v[82:85], v50, s[50:51] nt
	global_load_dwordx4 v[86:89], v51, s[50:51] nt
.Ldm8_nopfa:
	ds_read2_b32 v[122:123], v53 offset0:0 offset1:33
	ds_read2_b32 v[124:125], v53 offset0:66 offset1:99
	ds_read2_b32 v[126:127], v53 offset0:132 offset1:165
	ds_read2_b32 v[128:129], v53 offset0:198 offset1:231
	ds_read2_b32 v[130:131], v53 offset0:8 offset1:41
	ds_read2_b32 v[132:133], v53 offset0:74 offset1:107
	ds_read2_b32 v[134:135], v53 offset0:140 offset1:173
	ds_read2_b32 v[136:137], v53 offset0:206 offset1:239
	ds_read2_b32 v[138:139], v53 offset0:16 offset1:49
	ds_read2_b32 v[140:141], v53 offset0:82 offset1:115
	ds_read2_b32 v[142:143], v53 offset0:148 offset1:181
	ds_read2_b32 v[144:145], v53 offset0:214 offset1:247
	ds_read2_b32 v[146:147], v53 offset0:24 offset1:57
	ds_read2_b32 v[148:149], v53 offset0:90 offset1:123
	ds_read2_b32 v[180:181], v53 offset0:156 offset1:189
	ds_read2_b32 v[182:183], v53 offset0:222 offset1:255
	s_waitcnt lgkmcnt(0)
	v_cvt_pk_bf16_f32 v184, v122, v123
	v_cvt_pk_bf16_f32 v185, v124, v125
	v_cvt_pk_bf16_f32 v186, v126, v127
	v_cvt_pk_bf16_f32 v187, v128, v129
	v_cvt_pk_bf16_f32 v188, v130, v131
	v_cvt_pk_bf16_f32 v189, v132, v133
	v_cvt_pk_bf16_f32 v190, v134, v135
	v_cvt_pk_bf16_f32 v191, v136, v137
	v_cvt_pk_bf16_f32 v192, v138, v139
	v_cvt_pk_bf16_f32 v193, v140, v141
	v_cvt_pk_bf16_f32 v194, v142, v143
	v_cvt_pk_bf16_f32 v195, v144, v145
	v_cvt_pk_bf16_f32 v196, v146, v147
	v_cvt_pk_bf16_f32 v197, v148, v149
	v_cvt_pk_bf16_f32 v198, v180, v181
	v_cvt_pk_bf16_f32 v199, v182, v183
	v_add_u32_e32 v200, s58, v54
	v_add_u32_e32 v201, s58, v55
	v_add_u32_e32 v202, s58, v56
	v_add_u32_e32 v203, s58, v57
	global_store_dwordx4 v200, v[184:187], s[88:89]
	global_store_dwordx4 v201, v[188:191], s[88:89]
	global_store_dwordx4 v202, v[192:195], s[88:89]
	global_store_dwordx4 v203, v[196:199], s[88:89]
	s_cmp_ge_u32 s71, 0x2000
	s_cbranch_scc1 .Ldm8_jobend
	s_cmp_ge_u32 s91, 0x2000
	s_cbranch_scc1 .Ldm8_w4a
	s_waitcnt vmcnt(12)
	s_branch .Ldm8_goa

.Ldm8_goa:
	s_lshr_b32 s72, s71, 6
	s_and_b32 s73, s71, 63
	s_lshl_b32 s58, s73, 19
	s_lshl_b32 s59, s72, 7
	s_add_u32 s58, s58, s59
	ds_write_b32 v52, v90 offset:0
	ds_write_b32 v52, v91 offset:4
	ds_write_b32 v52, v92 offset:8
	ds_write_b32 v52, v93 offset:12
	ds_write_b32 v52, v94 offset:1056
	ds_write_b32 v52, v95 offset:1060
	ds_write_b32 v52, v96 offset:1064
	ds_write_b32 v52, v97 offset:1068
	ds_write_b32 v52, v98 offset:2112
	ds_write_b32 v52, v99 offset:2116
	ds_write_b32 v52, v100 offset:2120
	ds_write_b32 v52, v101 offset:2124
	ds_write_b32 v52, v102 offset:3168
	ds_write_b32 v52, v103 offset:3172
	ds_write_b32 v52, v104 offset:3176
	ds_write_b32 v52, v105 offset:3180
	ds_write_b32 v52, v106 offset:4224
	ds_write_b32 v52, v107 offset:4228
	ds_write_b32 v52, v108 offset:4232
	ds_write_b32 v52, v109 offset:4236
	ds_write_b32 v52, v110 offset:5280
	ds_write_b32 v52, v111 offset:5284
	ds_write_b32 v52, v112 offset:5288
	ds_write_b32 v52, v113 offset:5292
	ds_write_b32 v52, v114 offset:6336
	ds_write_b32 v52, v115 offset:6340
	ds_write_b32 v52, v116 offset:6344
	ds_write_b32 v52, v117 offset:6348
	ds_write_b32 v52, v118 offset:7392
	ds_write_b32 v52, v119 offset:7396
	ds_write_b32 v52, v120 offset:7400
	ds_write_b32 v52, v121 offset:7404
	s_waitcnt lgkmcnt(0)
	s_add_u32 s71, s91, s92
	s_cmp_ge_u32 s71, 0x2000
	s_cbranch_scc1 .Ldm8_nopfb
	s_lshr_b32 s72, s71, 6
	s_and_b32 s73, s71, 63
	s_lshl_b32 s56, s72, 19
	s_lshl_b32 s57, s73, 7
	s_add_u32 s56, s56, s57
	s_add_u32 s50, s6, s56
	s_addc_u32 s51, s7, 0
	global_load_dwordx4 v[90:93], v44, s[50:51] nt
	global_load_dwordx4 v[94:97], v45, s[50:51] nt
	global_load_dwordx4 v[98:101], v46, s[50:51] nt
	global_load_dwordx4 v[102:105], v47, s[50:51] nt
	global_load_dwordx4 v[106:109], v48, s[50:51] nt
	global_load_dwordx4 v[110:113], v49, s[50:51] nt
	global_load_dwordx4 v[114:117], v50, s[50:51] nt
	global_load_dwordx4 v[118:121], v51, s[50:51] nt
.Ldm8_nopfb:
	ds_read2_b32 v[122:123], v53 offset0:0 offset1:33
	ds_read2_b32 v[124:125], v53 offset0:66 offset1:99
	ds_read2_b32 v[126:127], v53 offset0:132 offset1:165
	ds_read2_b32 v[128:129], v53 offset0:198 offset1:231
	ds_read2_b32 v[130:131], v53 offset0:8 offset1:41
	ds_read2_b32 v[132:133], v53 offset0:74 offset1:107
	ds_read2_b32 v[134:135], v53 offset0:140 offset1:173
	ds_read2_b32 v[136:137], v53 offset0:206 offset1:239
	ds_read2_b32 v[138:139], v53 offset0:16 offset1:49
	ds_read2_b32 v[140:141], v53 offset0:82 offset1:115
	ds_read2_b32 v[142:143], v53 offset0:148 offset1:181
	ds_read2_b32 v[144:145], v53 offset0:214 offset1:247
	ds_read2_b32 v[146:147], v53 offset0:24 offset1:57
	ds_read2_b32 v[148:149], v53 offset0:90 offset1:123
	ds_read2_b32 v[180:181], v53 offset0:156 offset1:189
	ds_read2_b32 v[182:183], v53 offset0:222 offset1:255
	s_waitcnt lgkmcnt(0)
	v_cvt_pk_bf16_f32 v184, v122, v123
	v_cvt_pk_bf16_f32 v185, v124, v125
	v_cvt_pk_bf16_f32 v186, v126, v127
	v_cvt_pk_bf16_f32 v187, v128, v129
	v_cvt_pk_bf16_f32 v188, v130, v131
	v_cvt_pk_bf16_f32 v189, v132, v133
	v_cvt_pk_bf16_f32 v190, v134, v135
	v_cvt_pk_bf16_f32 v191, v136, v137
	v_cvt_pk_bf16_f32 v192, v138, v139
	v_cvt_pk_bf16_f32 v193, v140, v141
	v_cvt_pk_bf16_f32 v194, v142, v143
	v_cvt_pk_bf16_f32 v195, v144, v145
	v_cvt_pk_bf16_f32 v196, v146, v147
	v_cvt_pk_bf16_f32 v197, v148, v149
	v_cvt_pk_bf16_f32 v198, v180, v181
	v_cvt_pk_bf16_f32 v199, v182, v183
	v_add_u32_e32 v200, s58, v54
	v_add_u32_e32 v201, s58, v55
	v_add_u32_e32 v202, s58, v56
	v_add_u32_e32 v203, s58, v57
	global_store_dwordx4 v200, v[184:187], s[88:89]
	global_store_dwordx4 v201, v[188:191], s[88:89]
	global_store_dwordx4 v202, v[192:195], s[88:89]
	global_store_dwordx4 v203, v[196:199], s[88:89]
	s_cmp_ge_u32 s91, 0x2000
	s_cbranch_scc1 .Ldm8_jobend
	s_cmp_ge_u32 s71, 0x2000
	s_cbranch_scc1 .Ldm8_w4b
	s_waitcnt vmcnt(12)
	s_branch .Ldm8_gob

.Ldm8_done:
	s_mov_b64 exec, s[98:99]
	s_mov_b64 s[98:99], exec
	s_mov_b64 exec, -1
	v_readlane_b32 s2, v254, 0
	v_readlane_b32 s3, v255, 24
	s_load_dword s4, s[86:87], 0xc0
	s_waitcnt lgkmcnt(0)
	s_cmp_eq_u32 s3, 1
	s_cbranch_scc0 .Ldm7_sel0
	s_mov_b32 s69, 2
	s_mov_b32 s79, 3
	s_branch .Ldm7_go

.Ldm7_all:
	v_readfirstlane_b32 s5, v0
	s_lshr_b32 s5, s5, 6
	s_lshl_b32 s2, s2, 3
	s_add_u32 s2, s2, s5
	s_lshl_b32 s92, s4, 3
	v_mbcnt_lo_u32_b32 v41, -1, 0
	v_mbcnt_hi_u32_b32 v41, -1, v41
	v_lshrrev_b32_e32 v42, 3, v41
	v_and_b32_e32 v43, 7, v41
	v_lshlrev_b32_e32 v44, 15, v42
	v_lshl_add_u32 v44, v43, 4, v44
	v_add_u32_e32 v45, 0x40000, v44
	v_add_u32_e32 v46, 0x80000, v44
	v_add_u32_e32 v47, 0xc0000, v44
	v_add_u32_e32 v48, 0x100000, v44
	v_add_u32_e32 v49, 0x140000, v44
	v_add_u32_e32 v50, 0x180000, v44
	v_add_u32_e32 v51, 0x1c0000, v44
	s_lshl_b32 s49, s5, 14
	v_mul_u32_u24_e32 v52, 0x84, v42
	v_lshl_add_u32 v52, v43, 4, v52
	v_add_u32_e32 v52, s49, v52
	v_mul_u32_u24_e32 v53, 0x420, v43
	v_lshl_add_u32 v53, v42, 2, v53
	v_add_u32_e32 v53, s49, v53
	v_lshlrev_b32_e32 v54, 12, v42
	v_lshl_add_u32 v54, v43, 4, v54
	v_add_u32_e32 v55, 0x8000, v54
	v_add_u32_e32 v56, 0x10000, v54
	v_add_u32_e32 v57, 0x18000, v54
	v_lshlrev_b32_e32 v204, 2, v42
.Ldm7_job:
	s_mov_b32 s91, s2
	s_cmp_ge_u32 s91, 0x2000
	s_cbranch_scc1 .Ldm7_done
	s_load_dwordx2 s[6:7], s[86:87], 0x90
	s_load_dwordx2 s[88:89], s[86:87], 0xb0
	s_load_dwordx2 s[74:75], s[86:87], 0x88
	s_lshl_b32 s48, s69, 26
	s_waitcnt lgkmcnt(0)
	s_add_u32 s6, s6, s48
	s_addc_u32 s7, s7, 0
	s_lshl_b32 s48, s69, 25
	s_add_u32 s88, s88, 0x6eb32000
	s_addc_u32 s89, s89, 0
	s_add_u32 s88, s88, s48
	s_addc_u32 s89, s89, 0
	s_lshl_b32 s48, s69, 13
	s_add_u32 s74, s74, s48
	s_addc_u32 s75, s75, 0
	s_lshr_b32 s72, s91, 8
	s_and_b32 s73, s91, 255
	s_lshl_b32 s56, s72, 21
	s_lshl_b32 s57, s73, 7
	s_add_u32 s56, s56, s57
	s_add_u32 s50, s6, s56
	s_addc_u32 s51, s7, 0
	global_load_dwordx4 v[58:61], v44, s[50:51] nt
	global_load_dwordx4 v[62:65], v45, s[50:51] nt
	global_load_dwordx4 v[66:69], v46, s[50:51] nt
	global_load_dwordx4 v[70:73], v47, s[50:51] nt
	global_load_dwordx4 v[74:77], v48, s[50:51] nt
	global_load_dwordx4 v[78:81], v49, s[50:51] nt
	global_load_dwordx4 v[82:85], v50, s[50:51] nt
	global_load_dwordx4 v[86:89], v51, s[50:51] nt
	s_lshl_b32 s56, s72, 8
	s_add_u32 s50, s74, s56
	s_addc_u32 s51, s75, 0
	global_load_dword v230, v204, s[50:51] offset:0
	global_load_dword v231, v204, s[50:51] offset:32
	global_load_dword v232, v204, s[50:51] offset:64
	global_load_dword v233, v204, s[50:51] offset:96
	global_load_dword v234, v204, s[50:51] offset:128
	global_load_dword v235, v204, s[50:51] offset:160
	global_load_dword v236, v204, s[50:51] offset:192
	global_load_dword v237, v204, s[50:51] offset:224
	s_add_u32 s71, s91, s92
	s_cmp_ge_u32 s71, 0x2000
	s_cbranch_scc1 .Ldm7_first0
	s_lshr_b32 s72, s71, 8
	s_and_b32 s73, s71, 255
	s_lshl_b32 s56, s72, 21
	s_lshl_b32 s57, s73, 7
	s_add_u32 s56, s56, s57
	s_add_u32 s50, s6, s56
	s_addc_u32 s51, s7, 0
	global_load_dwordx4 v[90:93], v44, s[50:51] nt
	global_load_dwordx4 v[94:97], v45, s[50:51] nt
	global_load_dwordx4 v[98:101], v46, s[50:51] nt
	global_load_dwordx4 v[102:105], v47, s[50:51] nt
	global_load_dwordx4 v[106:109], v48, s[50:51] nt
	global_load_dwordx4 v[110:113], v49, s[50:51] nt
	global_load_dwordx4 v[114:117], v50, s[50:51] nt
	global_load_dwordx4 v[118:121], v51, s[50:51] nt
	s_lshl_b32 s56, s72, 8
	s_add_u32 s50, s74, s56
	s_addc_u32 s51, s75, 0
	global_load_dword v238, v204, s[50:51] offset:0
	global_load_dword v239, v204, s[50:51] offset:32
	global_load_dword v240, v204, s[50:51] offset:64
	global_load_dword v241, v204, s[50:51] offset:96
	global_load_dword v242, v204, s[50:51] offset:128
	global_load_dword v243, v204, s[50:51] offset:160
	global_load_dword v244, v204, s[50:51] offset:192
	global_load_dword v245, v204, s[50:51] offset:224
	s_waitcnt vmcnt(16)
	s_branch .Ldm7_loop

.Ldm7_loop:
	s_lshr_b32 s72, s91, 8
	s_and_b32 s73, s91, 255
	s_lshl_b32 s58, s73, 17
	s_lshl_b32 s59, s72, 7
	s_add_u32 s58, s58, s59
	v_mul_f32_e32 v58, v58, v230
	v_mul_f32_e32 v59, v59, v230
	v_mul_f32_e32 v60, v60, v230
	v_mul_f32_e32 v61, v61, v230
	v_mul_f32_e32 v62, v62, v231
	v_mul_f32_e32 v63, v63, v231
	v_mul_f32_e32 v64, v64, v231
	v_mul_f32_e32 v65, v65, v231
	v_mul_f32_e32 v66, v66, v232
	v_mul_f32_e32 v67, v67, v232
	v_mul_f32_e32 v68, v68, v232
	v_mul_f32_e32 v69, v69, v232
	v_mul_f32_e32 v70, v70, v233
	v_mul_f32_e32 v71, v71, v233
	v_mul_f32_e32 v72, v72, v233
	v_mul_f32_e32 v73, v73, v233
	v_mul_f32_e32 v74, v74, v234
	v_mul_f32_e32 v75, v75, v234
	v_mul_f32_e32 v76, v76, v234
	v_mul_f32_e32 v77, v77, v234
	v_mul_f32_e32 v78, v78, v235
	v_mul_f32_e32 v79, v79, v235
	v_mul_f32_e32 v80, v80, v235
	v_mul_f32_e32 v81, v81, v235
	v_mul_f32_e32 v82, v82, v236
	v_mul_f32_e32 v83, v83, v236
	v_mul_f32_e32 v84, v84, v236
	v_mul_f32_e32 v85, v85, v236
	v_mul_f32_e32 v86, v86, v237
	v_mul_f32_e32 v87, v87, v237
	v_mul_f32_e32 v88, v88, v237
	v_mul_f32_e32 v89, v89, v237
	ds_write_b32 v52, v58 offset:0
	ds_write_b32 v52, v59 offset:4
	ds_write_b32 v52, v60 offset:8
	ds_write_b32 v52, v61 offset:12
	ds_write_b32 v52, v62 offset:1056
	ds_write_b32 v52, v63 offset:1060
	ds_write_b32 v52, v64 offset:1064
	ds_write_b32 v52, v65 offset:1068
	ds_write_b32 v52, v66 offset:2112
	ds_write_b32 v52, v67 offset:2116
	ds_write_b32 v52, v68 offset:2120
	ds_write_b32 v52, v69 offset:2124
	ds_write_b32 v52, v70 offset:3168
	ds_write_b32 v52, v71 offset:3172
	ds_write_b32 v52, v72 offset:3176
	ds_write_b32 v52, v73 offset:3180
	ds_write_b32 v52, v74 offset:4224
	ds_write_b32 v52, v75 offset:4228
	ds_write_b32 v52, v76 offset:4232
	ds_write_b32 v52, v77 offset:4236
	ds_write_b32 v52, v78 offset:5280
	ds_write_b32 v52, v79 offset:5284
	ds_write_b32 v52, v80 offset:5288
	ds_write_b32 v52, v81 offset:5292
	ds_write_b32 v52, v82 offset:6336
	ds_write_b32 v52, v83 offset:6340
	ds_write_b32 v52, v84 offset:6344
	ds_write_b32 v52, v85 offset:6348
	ds_write_b32 v52, v86 offset:7392
	ds_write_b32 v52, v87 offset:7396
	ds_write_b32 v52, v88 offset:7400
	ds_write_b32 v52, v89 offset:7404
	s_waitcnt lgkmcnt(0)
	s_add_u32 s91, s71, s92
	s_cmp_ge_u32 s91, 0x2000
	s_cbranch_scc1 .Ldm7_nopfa
	s_lshr_b32 s72, s91, 8
	s_and_b32 s73, s91, 255
	s_lshl_b32 s56, s72, 21
	s_lshl_b32 s57, s73, 7
	s_add_u32 s56, s56, s57
	s_add_u32 s50, s6, s56
	s_addc_u32 s51, s7, 0
	global_load_dwordx4 v[58:61], v44, s[50:51] nt
	global_load_dwordx4 v[62:65], v45, s[50:51] nt
	global_load_dwordx4 v[66:69], v46, s[50:51] nt
	global_load_dwordx4 v[70:73], v47, s[50:51] nt
	global_load_dwordx4 v[74:77], v48, s[50:51] nt
	global_load_dwordx4 v[78:81], v49, s[50:51] nt
	global_load_dwordx4 v[82:85], v50, s[50:51] nt
	global_load_dwordx4 v[86:89], v51, s[50:51] nt
	s_lshl_b32 s56, s72, 8
	s_add_u32 s50, s74, s56
	s_addc_u32 s51, s75, 0
	global_load_dword v230, v204, s[50:51] offset:0
	global_load_dword v231, v204, s[50:51] offset:32
	global_load_dword v232, v204, s[50:51] offset:64
	global_load_dword v233, v204, s[50:51] offset:96
	global_load_dword v234, v204, s[50:51] offset:128
	global_load_dword v235, v204, s[50:51] offset:160
	global_load_dword v236, v204, s[50:51] offset:192
	global_load_dword v237, v204, s[50:51] offset:224
.Ldm7_nopfa:
	ds_read2_b32 v[122:123], v53 offset0:0 offset1:33
	ds_read2_b32 v[124:125], v53 offset0:66 offset1:99
	ds_read2_b32 v[126:127], v53 offset0:132 offset1:165
	ds_read2_b32 v[128:129], v53 offset0:198 offset1:231
	ds_read2_b32 v[130:131], v53 offset0:8 offset1:41
	ds_read2_b32 v[132:133], v53 offset0:74 offset1:107
	ds_read2_b32 v[134:135], v53 offset0:140 offset1:173
	ds_read2_b32 v[136:137], v53 offset0:206 offset1:239
	ds_read2_b32 v[138:139], v53 offset0:16 offset1:49
	ds_read2_b32 v[140:141], v53 offset0:82 offset1:115
	ds_read2_b32 v[142:143], v53 offset0:148 offset1:181
	ds_read2_b32 v[144:145], v53 offset0:214 offset1:247
	ds_read2_b32 v[146:147], v53 offset0:24 offset1:57
	ds_read2_b32 v[148:149], v53 offset0:90 offset1:123
	ds_read2_b32 v[180:181], v53 offset0:156 offset1:189
	ds_read2_b32 v[182:183], v53 offset0:222 offset1:255
	s_waitcnt lgkmcnt(0)
	v_cvt_pk_bf16_f32 v184, v122, v123
	v_cvt_pk_bf16_f32 v185, v124, v125
	v_cvt_pk_bf16_f32 v186, v126, v127
	v_cvt_pk_bf16_f32 v187, v128, v129
	v_cvt_pk_bf16_f32 v188, v130, v131
	v_cvt_pk_bf16_f32 v189, v132, v133
	v_cvt_pk_bf16_f32 v190, v134, v135
	v_cvt_pk_bf16_f32 v191, v136, v137
	v_cvt_pk_bf16_f32 v192, v138, v139
	v_cvt_pk_bf16_f32 v193, v140, v141
	v_cvt_pk_bf16_f32 v194, v142, v143
	v_cvt_pk_bf16_f32 v195, v144, v145
	v_cvt_pk_bf16_f32 v196, v146, v147
	v_cvt_pk_bf16_f32 v197, v148, v149
	v_cvt_pk_bf16_f32 v198, v180, v181
	v_cvt_pk_bf16_f32 v199, v182, v183
	v_add_u32_e32 v200, s58, v54
	v_add_u32_e32 v201, s58, v55
	v_add_u32_e32 v202, s58, v56
	v_add_u32_e32 v203, s58, v57
	global_store_dwordx4 v200, v[184:187], s[88:89]
	global_store_dwordx4 v201, v[188:191], s[88:89]
	global_store_dwordx4 v202, v[192:195], s[88:89]
	global_store_dwordx4 v203, v[196:199], s[88:89]
	s_cmp_ge_u32 s71, 0x2000
	s_cbranch_scc1 .Ldm7_jobend
	s_cmp_ge_u32 s91, 0x2000
	s_cbranch_scc1 .Ldm7_w4a
	s_waitcnt vmcnt(20)
	s_branch .Ldm7_goa

.Ldm7_goa:
	s_lshr_b32 s72, s71, 8
	s_and_b32 s73, s71, 255
	s_lshl_b32 s58, s73, 17
	s_lshl_b32 s59, s72, 7
	s_add_u32 s58, s58, s59
	v_mul_f32_e32 v90, v90, v238
	v_mul_f32_e32 v91, v91, v238
	v_mul_f32_e32 v92, v92, v238
	v_mul_f32_e32 v93, v93, v238
	v_mul_f32_e32 v94, v94, v239
	v_mul_f32_e32 v95, v95, v239
	v_mul_f32_e32 v96, v96, v239
	v_mul_f32_e32 v97, v97, v239
	v_mul_f32_e32 v98, v98, v240
	v_mul_f32_e32 v99, v99, v240
	v_mul_f32_e32 v100, v100, v240
	v_mul_f32_e32 v101, v101, v240
	v_mul_f32_e32 v102, v102, v241
	v_mul_f32_e32 v103, v103, v241
	v_mul_f32_e32 v104, v104, v241
	v_mul_f32_e32 v105, v105, v241
	v_mul_f32_e32 v106, v106, v242
	v_mul_f32_e32 v107, v107, v242
	v_mul_f32_e32 v108, v108, v242
	v_mul_f32_e32 v109, v109, v242
	v_mul_f32_e32 v110, v110, v243
	v_mul_f32_e32 v111, v111, v243
	v_mul_f32_e32 v112, v112, v243
	v_mul_f32_e32 v113, v113, v243
	v_mul_f32_e32 v114, v114, v244
	v_mul_f32_e32 v115, v115, v244
	v_mul_f32_e32 v116, v116, v244
	v_mul_f32_e32 v117, v117, v244
	v_mul_f32_e32 v118, v118, v245
	v_mul_f32_e32 v119, v119, v245
	v_mul_f32_e32 v120, v120, v245
	v_mul_f32_e32 v121, v121, v245
	ds_write_b32 v52, v90 offset:0
	ds_write_b32 v52, v91 offset:4
	ds_write_b32 v52, v92 offset:8
	ds_write_b32 v52, v93 offset:12
	ds_write_b32 v52, v94 offset:1056
	ds_write_b32 v52, v95 offset:1060
	ds_write_b32 v52, v96 offset:1064
	ds_write_b32 v52, v97 offset:1068
	ds_write_b32 v52, v98 offset:2112
	ds_write_b32 v52, v99 offset:2116
	ds_write_b32 v52, v100 offset:2120
	ds_write_b32 v52, v101 offset:2124
	ds_write_b32 v52, v102 offset:3168
	ds_write_b32 v52, v103 offset:3172
	ds_write_b32 v52, v104 offset:3176
	ds_write_b32 v52, v105 offset:3180
	ds_write_b32 v52, v106 offset:4224
	ds_write_b32 v52, v107 offset:4228
	ds_write_b32 v52, v108 offset:4232
	ds_write_b32 v52, v109 offset:4236
	ds_write_b32 v52, v110 offset:5280
	ds_write_b32 v52, v111 offset:5284
	ds_write_b32 v52, v112 offset:5288
	ds_write_b32 v52, v113 offset:5292
	ds_write_b32 v52, v114 offset:6336
	ds_write_b32 v52, v115 offset:6340
	ds_write_b32 v52, v116 offset:6344
	ds_write_b32 v52, v117 offset:6348
	ds_write_b32 v52, v118 offset:7392
	ds_write_b32 v52, v119 offset:7396
	ds_write_b32 v52, v120 offset:7400
	ds_write_b32 v52, v121 offset:7404
	s_waitcnt lgkmcnt(0)
	s_add_u32 s71, s91, s92
	s_cmp_ge_u32 s71, 0x2000
	s_cbranch_scc1 .Ldm7_nopfb
	s_lshr_b32 s72, s71, 8
	s_and_b32 s73, s71, 255
	s_lshl_b32 s56, s72, 21
	s_lshl_b32 s57, s73, 7
	s_add_u32 s56, s56, s57
	s_add_u32 s50, s6, s56
	s_addc_u32 s51, s7, 0
	global_load_dwordx4 v[90:93], v44, s[50:51] nt
	global_load_dwordx4 v[94:97], v45, s[50:51] nt
	global_load_dwordx4 v[98:101], v46, s[50:51] nt
	global_load_dwordx4 v[102:105], v47, s[50:51] nt
	global_load_dwordx4 v[106:109], v48, s[50:51] nt
	global_load_dwordx4 v[110:113], v49, s[50:51] nt
	global_load_dwordx4 v[114:117], v50, s[50:51] nt
	global_load_dwordx4 v[118:121], v51, s[50:51] nt
	s_lshl_b32 s56, s72, 8
	s_add_u32 s50, s74, s56
	s_addc_u32 s51, s75, 0
	global_load_dword v238, v204, s[50:51] offset:0
	global_load_dword v239, v204, s[50:51] offset:32
	global_load_dword v240, v204, s[50:51] offset:64
	global_load_dword v241, v204, s[50:51] offset:96
	global_load_dword v242, v204, s[50:51] offset:128
	global_load_dword v243, v204, s[50:51] offset:160
	global_load_dword v244, v204, s[50:51] offset:192
	global_load_dword v245, v204, s[50:51] offset:224
.Ldm7_nopfb:
	ds_read2_b32 v[122:123], v53 offset0:0 offset1:33
	ds_read2_b32 v[124:125], v53 offset0:66 offset1:99
	ds_read2_b32 v[126:127], v53 offset0:132 offset1:165
	ds_read2_b32 v[128:129], v53 offset0:198 offset1:231
	ds_read2_b32 v[130:131], v53 offset0:8 offset1:41
	ds_read2_b32 v[132:133], v53 offset0:74 offset1:107
	ds_read2_b32 v[134:135], v53 offset0:140 offset1:173
	ds_read2_b32 v[136:137], v53 offset0:206 offset1:239
	ds_read2_b32 v[138:139], v53 offset0:16 offset1:49
	ds_read2_b32 v[140:141], v53 offset0:82 offset1:115
	ds_read2_b32 v[142:143], v53 offset0:148 offset1:181
	ds_read2_b32 v[144:145], v53 offset0:214 offset1:247
	ds_read2_b32 v[146:147], v53 offset0:24 offset1:57
	ds_read2_b32 v[148:149], v53 offset0:90 offset1:123
	ds_read2_b32 v[180:181], v53 offset0:156 offset1:189
	ds_read2_b32 v[182:183], v53 offset0:222 offset1:255
	s_waitcnt lgkmcnt(0)
	v_cvt_pk_bf16_f32 v184, v122, v123
	v_cvt_pk_bf16_f32 v185, v124, v125
	v_cvt_pk_bf16_f32 v186, v126, v127
	v_cvt_pk_bf16_f32 v187, v128, v129
	v_cvt_pk_bf16_f32 v188, v130, v131
	v_cvt_pk_bf16_f32 v189, v132, v133
	v_cvt_pk_bf16_f32 v190, v134, v135
	v_cvt_pk_bf16_f32 v191, v136, v137
	v_cvt_pk_bf16_f32 v192, v138, v139
	v_cvt_pk_bf16_f32 v193, v140, v141
	v_cvt_pk_bf16_f32 v194, v142, v143
	v_cvt_pk_bf16_f32 v195, v144, v145
	v_cvt_pk_bf16_f32 v196, v146, v147
	v_cvt_pk_bf16_f32 v197, v148, v149
	v_cvt_pk_bf16_f32 v198, v180, v181
	v_cvt_pk_bf16_f32 v199, v182, v183
	v_add_u32_e32 v200, s58, v54
	v_add_u32_e32 v201, s58, v55
	v_add_u32_e32 v202, s58, v56
	v_add_u32_e32 v203, s58, v57
	global_store_dwordx4 v200, v[184:187], s[88:89]
	global_store_dwordx4 v201, v[188:191], s[88:89]
	global_store_dwordx4 v202, v[192:195], s[88:89]
	global_store_dwordx4 v203, v[196:199], s[88:89]
	s_cmp_ge_u32 s91, 0x2000
	s_cbranch_scc1 .Ldm7_jobend
	s_cmp_ge_u32 s71, 0x2000
	s_cbranch_scc1 .Ldm7_w4b
	s_waitcnt vmcnt(20)
	s_branch .Ldm7_gob

.Ldm7_done:
	s_mov_b64 exec, s[98:99]

.LBB0_975:
	s_waitcnt vmcnt(0)
	v_readlane_b32 s54, v255, 36
	v_readlane_b32 s55, v255, 37
	s_barrier
	s_mov_b64 s[98:99], exec
	s_mov_b64 exec, -1
	v_readlane_b32 s2, v254, 0
	v_readlane_b32 s3, v255, 24
	s_load_dword s4, s[86:87], 0xc0
	s_waitcnt lgkmcnt(0)
	s_cmp_eq_u32 s3, 0
	s_cbranch_scc0 .Ldl8_sel0
	s_mov_b32 s69, 1
	s_mov_b32 s79, 2
	s_branch .Ldl8_go
.Ldl8_sel0:
	s_cmp_eq_u32 s3, 2
	s_cbranch_scc0 .Ldl8_sel1
	s_mov_b32 s69, 3
	s_mov_b32 s79, 4
	s_branch .Ldl8_go

.Ldl8_go:
	s_cmp_eq_u32 s4, 0x100
	s_cbranch_scc0 .Ldl8_all
	s_cmp_lt_u32 s2, 84
	s_cbranch_scc1 .Ldl8_done
	s_sub_u32 s2, s2, 84
	s_movk_i32 s4, 172

.Ldl8_done:
	s_mov_b64 exec, s[98:99]
	s_mov_b64 s[98:99], exec
	s_mov_b64 exec, -1
	v_readlane_b32 s2, v254, 0
	v_readlane_b32 s3, v255, 24
	s_load_dword s4, s[86:87], 0xc0
	s_waitcnt lgkmcnt(0)
	s_cmp_eq_u32 s3, 0
	s_cbranch_scc0 .Ldl7_sel0
	s_mov_b32 s69, 1
	s_mov_b32 s79, 2
	s_branch .Ldl7_go

.LBB0_1964:
	s_waitcnt vmcnt(0)
	v_readlane_b32 s86, v255, 26
	v_readlane_b32 s87, v255, 27
	s_barrier
	s_mov_b64 s[98:99], exec
	s_mov_b64 exec, -1
	v_readlane_b32 s2, v254, 0
	v_readlane_b32 s3, v255, 24
	s_load_dword s4, s[86:87], 0xc0
	s_load_dwordx2 s[6:7], s[86:87], 0x10
	s_load_dwordx2 s[88:89], s[86:87], 0xb0
	s_waitcnt lgkmcnt(0)
	s_cmp_eq_u32 s3, 0
	s_cbranch_scc0 .Ldck_sel0
	s_mov_b32 s91, 0x20000
	s_mov_b32 s79, 0x30000
	s_branch .Ldck_go
.Ldck_sel0:
	s_cmp_eq_u32 s3, 1
	s_cbranch_scc0 .Ldck_sel1
	s_mov_b32 s91, 0x30000
	s_mov_b32 s79, 0x40000
	s_branch .Ldck_go

.Ldck_go:
	s_cmp_eq_u32 s4, 0x100
	s_cbranch_scc0 .Ldck_all
	s_cmp_lt_u32 s2, 128
	s_cbranch_scc1 .Ldck_done
	s_sub_u32 s2, s2, 128
	s_movk_i32 s4, 128
.Ldck_all:
	v_readfirstlane_b32 s5, v0
	s_lshr_b32 s5, s5, 6
	s_lshl_b32 s2, s2, 3
	s_add_u32 s2, s2, s5
	s_lshl_b32 s92, s4, 3
	s_add_u32 s91, s91, s2
	s_add_u32 s88, s88, 0x27b32000
	s_addc_u32 s89, s89, 0
	v_mbcnt_lo_u32_b32 v41, -1, 0
	v_mbcnt_hi_u32_b32 v41, -1, v41
	v_lshlrev_b32_e32 v42, 5, v41
	v_lshlrev_b32_e32 v43, 4, v41
	s_cmp_ge_u32 s91, s79
	s_cbranch_scc1 .Ldck_done
.Ldck_batch:
	s_mov_b32 s71, s91
	s_cmp_ge_u32 s71, s79
	s_cbranch_scc1 .Ldck_ldend
	s_lshl_b32 s56, s71, 11
	s_add_u32 s50, s6, s56
	s_addc_u32 s51, s7, 0
	global_load_dwordx4 v[58:61], v42, s[50:51] nt
	global_load_dwordx4 v[62:65], v42, s[50:51] offset:16 nt
	s_add_u32 s71, s71, s92
	s_cmp_ge_u32 s71, s79
	s_cbranch_scc1 .Ldck_ldend
	s_lshl_b32 s56, s71, 11
	s_add_u32 s50, s6, s56
	s_addc_u32 s51, s7, 0
	global_load_dwordx4 v[66:69], v42, s[50:51] nt
	global_load_dwordx4 v[70:73], v42, s[50:51] offset:16 nt
	s_add_u32 s71, s71, s92
	s_cmp_ge_u32 s71, s79
	s_cbranch_scc1 .Ldck_ldend
	s_lshl_b32 s56, s71, 11
	s_add_u32 s50, s6, s56
	s_addc_u32 s51, s7, 0
	global_load_dwordx4 v[74:77], v42, s[50:51] nt
	global_load_dwordx4 v[78:81], v42, s[50:51] offset:16 nt
	s_add_u32 s71, s71, s92
	s_cmp_ge_u32 s71, s79
	s_cbranch_scc1 .Ldck_ldend
	s_lshl_b32 s56, s71, 11
	s_add_u32 s50, s6, s56
	s_addc_u32 s51, s7, 0
	global_load_dwordx4 v[82:85], v42, s[50:51] nt
	global_load_dwordx4 v[86:89], v42, s[50:51] offset:16 nt
	s_add_u32 s71, s71, s92
	s_cmp_ge_u32 s71, s79
	s_cbranch_scc1 .Ldck_ldend
	s_lshl_b32 s56, s71, 11
	s_add_u32 s50, s6, s56
	s_addc_u32 s51, s7, 0
	global_load_dwordx4 v[90:93], v42, s[50:51] nt
	global_load_dwordx4 v[94:97], v42, s[50:51] offset:16 nt
	s_add_u32 s71, s71, s92
	s_cmp_ge_u32 s71, s79
	s_cbranch_scc1 .Ldck_ldend
	s_lshl_b32 s56, s71, 11
	s_add_u32 s50, s6, s56
	s_addc_u32 s51, s7, 0
	global_load_dwordx4 v[98:101], v42, s[50:51] nt
	global_load_dwordx4 v[102:105], v42, s[50:51] offset:16 nt
	s_add_u32 s71, s71, s92
	s_cmp_ge_u32 s71, s79
	s_cbranch_scc1 .Ldck_ldend
	s_lshl_b32 s56, s71, 11
	s_add_u32 s50, s6, s56
	s_addc_u32 s51, s7, 0
	global_load_dwordx4 v[106:109], v42, s[50:51] nt
	global_load_dwordx4 v[110:113], v42, s[50:51] offset:16 nt
	s_add_u32 s71, s71, s92
	s_cmp_ge_u32 s71, s79
	s_cbranch_scc1 .Ldck_ldend
	s_lshl_b32 s56, s71, 11
	s_add_u32 s50, s6, s56
	s_addc_u32 s51, s7, 0
	global_load_dwordx4 v[114:117], v42, s[50:51] nt
	global_load_dwordx4 v[118:121], v42, s[50:51] offset:16 nt
	s_add_u32 s71, s71, s92
.Ldck_ldend:
	s_waitcnt vmcnt(0)
	s_mov_b32 s71, s91
	s_cmp_ge_u32 s71, s79
	s_cbranch_scc1 .Ldck_stend
	s_lshr_b32 s72, s71, 12
	s_and_b32 s73, s71, 0xfff
	s_mulk_i32 s72, 0x1100
	s_add_u32 s72, s72, s73
	s_mul_i32 s72, s72, 0x500
	s_add_u32 s50, s88, s72
	s_addc_u32 s51, s89, 0
	v_cvt_pk_bf16_f32 v122, v58, v59
	v_cvt_pk_bf16_f32 v123, v60, v61
	v_cvt_pk_bf16_f32 v124, v62, v63
	v_cvt_pk_bf16_f32 v125, v64, v65
	global_store_dwordx4 v43, v[122:125], s[50:51]
	s_add_u32 s71, s71, s92
	s_cmp_ge_u32 s71, s79
	s_cbranch_scc1 .Ldck_stend
	s_lshr_b32 s72, s71, 12
	s_and_b32 s73, s71, 0xfff
	s_mulk_i32 s72, 0x1100
	s_add_u32 s72, s72, s73
	s_mul_i32 s72, s72, 0x500
	s_add_u32 s50, s88, s72
	s_addc_u32 s51, s89, 0
	v_cvt_pk_bf16_f32 v126, v66, v67
	v_cvt_pk_bf16_f32 v127, v68, v69
	v_cvt_pk_bf16_f32 v128, v70, v71
	v_cvt_pk_bf16_f32 v129, v72, v73
	global_store_dwordx4 v43, v[126:129], s[50:51]
	s_add_u32 s71, s71, s92
	s_cmp_ge_u32 s71, s79
	s_cbranch_scc1 .Ldck_stend
	s_lshr_b32 s72, s71, 12
	s_and_b32 s73, s71, 0xfff
	s_mulk_i32 s72, 0x1100
	s_add_u32 s72, s72, s73
	s_mul_i32 s72, s72, 0x500
	s_add_u32 s50, s88, s72
	s_addc_u32 s51, s89, 0
	v_cvt_pk_bf16_f32 v130, v74, v75
	v_cvt_pk_bf16_f32 v131, v76, v77
	v_cvt_pk_bf16_f32 v132, v78, v79
	v_cvt_pk_bf16_f32 v133, v80, v81
	global_store_dwordx4 v43, v[130:133], s[50:51]
	s_add_u32 s71, s71, s92
	s_cmp_ge_u32 s71, s79
	s_cbranch_scc1 .Ldck_stend
	s_lshr_b32 s72, s71, 12
	s_and_b32 s73, s71, 0xfff
	s_mulk_i32 s72, 0x1100
	s_add_u32 s72, s72, s73
	s_mul_i32 s72, s72, 0x500
	s_add_u32 s50, s88, s72
	s_addc_u32 s51, s89, 0
	v_cvt_pk_bf16_f32 v134, v82, v83
	v_cvt_pk_bf16_f32 v135, v84, v85
	v_cvt_pk_bf16_f32 v136, v86, v87
	v_cvt_pk_bf16_f32 v137, v88, v89
	global_store_dwordx4 v43, v[134:137], s[50:51]
	s_add_u32 s71, s71, s92
	s_cmp_ge_u32 s71, s79
	s_cbranch_scc1 .Ldck_stend
	s_lshr_b32 s72, s71, 12
	s_and_b32 s73, s71, 0xfff
	s_mulk_i32 s72, 0x1100
	s_add_u32 s72, s72, s73
	s_mul_i32 s72, s72, 0x500
	s_add_u32 s50, s88, s72
	s_addc_u32 s51, s89, 0
	v_cvt_pk_bf16_f32 v138, v90, v91
	v_cvt_pk_bf16_f32 v139, v92, v93
	v_cvt_pk_bf16_f32 v140, v94, v95
	v_cvt_pk_bf16_f32 v141, v96, v97
	global_store_dwordx4 v43, v[138:141], s[50:51]
	s_add_u32 s71, s71, s92
	s_cmp_ge_u32 s71, s79
	s_cbranch_scc1 .Ldck_stend
	s_lshr_b32 s72, s71, 12
	s_and_b32 s73, s71, 0xfff
	s_mulk_i32 s72, 0x1100
	s_add_u32 s72, s72, s73
	s_mul_i32 s72, s72, 0x500
	s_add_u32 s50, s88, s72
	s_addc_u32 s51, s89, 0
	v_cvt_pk_bf16_f32 v142, v98, v99
	v_cvt_pk_bf16_f32 v143, v100, v101
	v_cvt_pk_bf16_f32 v144, v102, v103
	v_cvt_pk_bf16_f32 v145, v104, v105
	global_store_dwordx4 v43, v[142:145], s[50:51]
	s_add_u32 s71, s71, s92
	s_cmp_ge_u32 s71, s79
	s_cbranch_scc1 .Ldck_stend
	s_lshr_b32 s72, s71, 12
	s_and_b32 s73, s71, 0xfff
	s_mulk_i32 s72, 0x1100
	s_add_u32 s72, s72, s73
	s_mul_i32 s72, s72, 0x500
	s_add_u32 s50, s88, s72
	s_addc_u32 s51, s89, 0
	v_cvt_pk_bf16_f32 v146, v106, v107
	v_cvt_pk_bf16_f32 v147, v108, v109
	v_cvt_pk_bf16_f32 v148, v110, v111
	v_cvt_pk_bf16_f32 v149, v112, v113
	global_store_dwordx4 v43, v[146:149], s[50:51]
	s_add_u32 s71, s71, s92
	s_cmp_ge_u32 s71, s79
	s_cbranch_scc1 .Ldck_stend
	s_lshr_b32 s72, s71, 12
	s_and_b32 s73, s71, 0xfff
	s_mulk_i32 s72, 0x1100
	s_add_u32 s72, s72, s73
	s_mul_i32 s72, s72, 0x500
	s_add_u32 s50, s88, s72
	s_addc_u32 s51, s89, 0
	v_cvt_pk_bf16_f32 v180, v114, v115
	v_cvt_pk_bf16_f32 v181, v116, v117
	v_cvt_pk_bf16_f32 v182, v118, v119
	v_cvt_pk_bf16_f32 v183, v120, v121
	global_store_dwordx4 v43, v[180:183], s[50:51]
	s_add_u32 s71, s71, s92
.Ldck_stend:
	s_lshl_b32 s56, s92, 3
	s_add_u32 s91, s91, s56
	s_cmp_lt_u32 s91, s79
	s_cbranch_scc1 .Ldck_batch
